# tile DMA issued only by waves 0-3 (8 each), waves 4-7 none; on top of best (S2 schedule + ccdma + prio S1 + P0 transposes)
# baseline (speedup 1.0000x reference)
; #define GLOAD(t_, slotoff_) do { const char* kb_ = KGc + ((size_t)(t_) << 14); const char* vb_ = VGc + ((size_t)(t_) << 14); \
;         const unsigned d_ = (unsigned)__builtin_amdgcn_readfirstlane((int)(ldsbase + (slotoff_) + wid * 1024)); \
;         GLDS16(kb_, d_); GLDS16(kb_ + 8192, d_ + 8192u); GLDS16(vb_, d_ + 16384u); GLDS16(vb_ + 8192, d_ + 24576u); } while (0)
; DI void attn_unit(const Params& p, int bh, int qb, char* lds, float lam, int tid, int lane, int wid, const bool build_tab) {
;     ...
;             asm volatile("s_waitcnt vmcnt(0)" ::: "memory");
;             if (t + 2 < NT) GLOAD(t + 2, sn2);
.LBB0_357:
	s_setprio 0
	s_waitcnt vmcnt(0)
	s_cmp_ge_u32 s7, s77
	s_cbranch_scc1 .LBB0_359
	s_cmp_ge_u32 s59, 64
	s_cbranch_scc1 .LBB0_359
	s_add_i32 s92, s82, s93
	s_mov_b32 m0, s92
	v_lshl_add_u64 v[242:243], v[200:201], 0, s[26:27]
	global_load_lds_dwordx4 v[200:201], off
	global_load_lds_dwordx4 v[200:201], off offset:1024
	global_load_lds_dwordx4 v[200:201], off offset:2048
	global_load_lds_dwordx4 v[200:201], off offset:3072
	s_add_i32 s92, s92, 0x4000
	s_mov_b32 m0, s92
	s_nop 0
	global_load_lds_dwordx4 v[242:243], off
	global_load_lds_dwordx4 v[242:243], off offset:1024
	global_load_lds_dwordx4 v[242:243], off offset:2048
	global_load_lds_dwordx4 v[242:243], off offset:3072

; #define GLOAD(t_, slotoff_) do { const char* kb_ = KGc + ((size_t)(t_) << 14); const char* vb_ = VGc + ((size_t)(t_) << 14); \
;         const unsigned d_ = (unsigned)__builtin_amdgcn_readfirstlane((int)(ldsbase + (slotoff_) + wid * 1024)); \
;         GLDS16(kb_, d_); GLDS16(kb_ + 8192, d_ + 8192u); GLDS16(vb_, d_ + 16384u); GLDS16(vb_ + 8192, d_ + 24576u); } while (0)
; DI void attn_unit(const Params& p, int bh, int qb, char* lds, float lam, int tid, int lane, int wid, const bool build_tab) {
;     ...
;             asm volatile("s_waitcnt vmcnt(0)" ::: "memory");
;             if (t + 2 < NT) GLOAD(t + 2, sn2);
.LBB0_377:
	s_setprio 0
	s_waitcnt vmcnt(0)
	s_cmp_ge_u32 s51, s55
	s_cbranch_scc1 .LBB0_379
	s_cmp_ge_u32 s59, 64
	s_cbranch_scc1 .LBB0_379
	s_add_i32 s92, s67, s93
	s_mov_b32 m0, s92
	v_lshl_add_u64 v[244:245], v[174:175], 0, s[26:27]
	global_load_lds_dwordx4 v[174:175], off
	global_load_lds_dwordx4 v[174:175], off offset:1024
	global_load_lds_dwordx4 v[174:175], off offset:2048
	global_load_lds_dwordx4 v[174:175], off offset:3072
	s_add_i32 s92, s92, 0x4000
	s_mov_b32 m0, s92
	s_nop 0
	global_load_lds_dwordx4 v[244:245], off
	global_load_lds_dwordx4 v[244:245], off offset:1024
	global_load_lds_dwordx4 v[244:245], off offset:2048
	global_load_lds_dwordx4 v[244:245], off offset:3072
